# counted waits in the P1 norm1 loop: per-iteration bias load and its full drain hoisted out of the loop, loop-top wait ladder replaced by one pre-loop wait, row-copy waits count the younger stores
# speedup vs baseline: 1.0028x; 1.0013x over previous
; __device__ __forceinline__ void phase1(const Params& p, LAS unsigned char* lds, int tid, int lane, int wave) {
;     ...
;     for (int i = tid; i < 8192; i += 512) { const int k = i >> 3, h = i & 7; wf[h * 1024 + k] = p.w_in[(size_t)k * DIN + 1536 + h]; }
;     __syncthreads();
;     bf16_t* hb = (bf16_t*)(p.ws + WS_H); float* logf = (float*)(p.ws + WS_LOGF);
;     const int gw = blockIdx.x * 8 + wave, NGW = gridDim.x * 8;
;     const int rpw = (((T_ + NGW - 1) / NGW) + 1) & ~1  , r0 = gw * rpw, r1 = (r0 + rpw < T_) ? r0 + rpw : T_;
;     const bool b5 = (lane & 32) != 0, b4 = (lane & 16) != 0, b3 = (lane & 8) != 0;
;     f32x4 gmv[4], shv[4]; int bcur = -1;
;     f32x4 vn[2][4];
;     ...
;     if (r0 < r1) {
; #pragma unroll
;         for (int q = 0; q < 2; ++q)
; #pragma unroll
;             for (int j = 0; j < 4; ++j) vn[q][j] = __builtin_nontemporal_load((const f32x4*)(p.x + (size_t)ROW2(r0, q) * D_ + 4 * lane + 256 * j)); }
;     ...
;         f32x4 v[2][4]; float ss[2];
; #pragma unroll
;         for (int q = 0; q < 2; ++q) { ss[q] = 0.f;
; #pragma unroll
;             for (int j = 0; j < 4; ++j) { v[q][j] = vn[q][j]; ss[q] += (v[q][j].x * v[q][j].x + v[q][j].y * v[q][j].y) + (v[q][j].z * v[q][j].z + v[q][j].w * v[q][j].w); } }
;         if (row + 2 < r1) {
; #pragma unroll
;             for (int q = 0; q < 2; ++q)
; #pragma unroll
;                 for (int j = 0; j < 4; ++j) vn[q][j] = __builtin_nontemporal_load((const f32x4*)(p.x + (size_t)ROW2(row + 2, q) * D_ + 4 * lane + 256 * j)); }
.LBB0_192:
	s_or_b64 exec, exec, s[6:7]
	s_lshl_b32 s0, s26, 3
	s_abs_i32 s1, s0
	v_cvt_f32_u32_e32 v0, s1
	s_sub_i32 s6, 0, s1
	s_add_i32 s5, s0, 0x3fff
	s_xor_b32 s0, s5, s0
	v_rcp_iflag_f32_e32 v0, v0
	s_abs_i32 s5, s5
	s_lshl_b32 s4, s2, 3
	s_add_i32 s4, s58, s4
	v_mul_f32_e32 v0, 0x4f7ffffe, v0
	v_cvt_u32_f32_e32 v0, v0
	s_ashr_i32 s0, s0, 31
	v_mbcnt_lo_u32_b32 v209, -1, 0
	s_waitcnt lgkmcnt(0)
	v_readfirstlane_b32 s7, v0
	s_mul_i32 s6, s6, s7
	s_mul_hi_u32 s6, s7, s6
	s_add_i32 s7, s7, s6
	s_mul_hi_u32 s6, s5, s7
	s_mul_i32 s7, s6, s1
	s_sub_i32 s5, s5, s7
	s_add_i32 s7, s6, 1
	s_sub_i32 s8, s5, s1
	s_cmp_ge_u32 s5, s1
	s_cselect_b32 s6, s7, s6
	s_cselect_b32 s5, s8, s5
	s_add_i32 s7, s6, 1
	s_cmp_ge_u32 s5, s1
	s_cselect_b32 s1, s7, s6
	s_xor_b32 s1, s1, s0
	s_sub_i32 s0, s1, s0
	s_add_i32 s0, s0, 1
	s_and_b32 s0, s0, -2
	s_mul_i32 s14, s0, s4
	s_add_i32 s0, s14, s0
	s_min_i32 s4, s0, 0x4000
	v_cmp_gt_u32_e64 s[6:7], 32, v154
	s_cmp_ge_i32 s14, s4
	s_barrier
	s_cbranch_scc1 .LBB0_201
	s_ashr_i32 s15, s14, 31
	s_lshl_b64 s[16:17], s[14:15], 12
	s_or_b32 s0, s14, 1
	s_cmp_lt_i32 s0, s4
	v_mov_b32_e32 v99, 0
	v_lshlrev_b32_e32 v98, 4, v154
	s_cselect_b32 s8, s0, s14
	v_lshl_add_u64 v[100:101], s[34:35], 0, v[98:99]
	s_ashr_i32 s9, s8, 31
	v_lshl_add_u64 v[0:1], v[100:101], 0, s[16:17]
	s_lshl_b64 s[8:9], s[8:9], 12
	global_load_dwordx4 v[92:95], v[0:1], off nt
	global_load_dwordx4 v[88:91], v[0:1], off offset:1024 nt
	global_load_dwordx4 v[84:87], v[0:1], off offset:2048 nt
	global_load_dwordx4 v[80:83], v[0:1], off offset:3072 nt
	v_lshl_add_u64 v[0:1], v[100:101], 0, s[8:9]
	global_load_dwordx4 v[76:79], v[0:1], off nt
	global_load_dwordx4 v[72:75], v[0:1], off offset:1024 nt
	global_load_dwordx4 v[68:71], v[0:1], off offset:2048 nt
	global_load_dwordx4 v[64:67], v[0:1], off offset:3072 nt
	v_mbcnt_hi_u32_b32 v1, -1, v209
	v_and_b32_e32 v2, 64, v1
	v_add_u32_e32 v7, 64, v2
	v_lshrrev_b32_e32 v2, 1, v154
	v_and_b32_e32 v2, 28, v2
	v_mov_b32_e32 v3, v99
	v_lshl_add_u64 v[4:5], s[30:31], 0, v[2:3]
	s_mov_b64 s[18:19], 0x100000
	v_lshl_add_u64 v[102:103], v[4:5], 0, s[18:19]
	v_xor_b32_e32 v5, 4, v1
	v_cmp_lt_i32_e32 vcc, v5, v7
	v_lshlrev_b32_e32 v10, 3, v154
	v_mov_b32_e32 v11, v99
	v_cndmask_b32_e32 v5, v1, v5, vcc
	v_lshlrev_b32_e32 v97, 2, v5
	v_xor_b32_e32 v5, 8, v1
	v_cmp_lt_i32_e32 vcc, v5, v7
	v_lshl_add_u64 v[10:11], s[30:31], 0, v[10:11]
	s_mov_b64 s[20:21], 0x2000000
	v_cndmask_b32_e32 v5, v1, v5, vcc
	v_lshlrev_b32_e32 v117, 2, v5
	v_xor_b32_e32 v5, 16, v1
	v_lshl_add_u64 v[108:109], v[10:11], 0, s[20:21]
	s_lshl_b64 s[20:21], s[14:15], 5
	v_cmp_lt_i32_e32 vcc, v5, v7
	v_lshl_add_u64 v[106:107], s[36:37], 0, v[2:3]
	v_or_b32_e32 v2, s20, v2
	v_mov_b32_e32 v3, s21
	v_and_b32_e32 v0, 16, v208
	v_cndmask_b32_e32 v5, v1, v5, vcc
	v_lshl_add_u64 v[110:111], v[2:3], 0, s[18:19]
	s_lshl_b64 s[18:19], s[14:15], 11
	v_cmp_eq_u32_e64 s[8:9], 0, v0
	v_and_b32_e32 v0, 8, v208
	v_lshlrev_b32_e32 v122, 2, v5
	v_xor_b32_e32 v5, 32, v1
	s_add_u32 s16, s34, s16
	v_cmp_eq_u32_e64 s[10:11], 0, v0
	v_lshlrev_b32_e32 v0, 2, v154
	v_cmp_lt_i32_e32 vcc, v5, v7
	s_addc_u32 s17, s35, s17
	v_or_b32_e32 v4, 0x100, v0
	v_or_b32_e32 v6, 0x200, v0
	v_or_b32_e32 v8, 0x300, v0
	v_cndmask_b32_e32 v1, v1, v5, vcc
	v_lshl_add_u64 v[2:3], s[16:17], 0, v[98:99]
	s_mov_b64 s[16:17], 0x2000
	s_mov_b32 s40, -1
	v_cmp_eq_u32_e64 s[12:13], 0, v155
	v_lshlrev_b32_e32 v123, 2, v1
	v_lshl_add_u64 v[104:105], s[38:39], 0, v[98:99]
	v_lshl_or_b32 v112, v154, 3, s18
	v_mov_b32_e32 v113, s19
	v_lshl_add_u64 v[114:115], v[2:3], 0, s[16:17]
	s_mov_b64 s[18:19], 0x1000
	v_lshlrev_b32_e32 v99, 2, v0
	v_lshlrev_b32_e32 v124, 2, v4
	v_lshlrev_b32_e32 v125, 2, v6
	v_lshlrev_b32_e32 v126, 2, v8
	s_mov_b32 s20, 0x3a800000
	s_mov_b32 s5, 0x800000
	s_brev_b32 s21, 64
	s_mov_b32 s28, 0xbfb8aa3b
	s_mov_b32 s29, 0x3f317217
	s_mov_b32 s36, 0x7f800000
	v_mov_b32_e32 v116, 0x358637bd
	v_mov_b32_e32 v127, 0x41b17218
	global_load_dword v153, v[106:107], off
	s_waitcnt vmcnt(0)
	s_branch .LBB0_195
.LBB0_194:
	s_or_b64 exec, exec, s[34:35]
	s_waitcnt vmcnt(17)
	v_mov_b64_e32 v[94:95], v[34:35]
	s_waitcnt vmcnt(16)
	v_mov_b64_e32 v[90:91], v[38:39]
	s_waitcnt vmcnt(15)
	v_mov_b64_e32 v[86:87], v[42:43]
	s_waitcnt vmcnt(14)
	v_mov_b64_e32 v[82:83], v[46:47]
	s_waitcnt vmcnt(13)
	v_mov_b64_e32 v[78:79], v[50:51]
	s_waitcnt vmcnt(12)
	v_mov_b64_e32 v[74:75], v[54:55]
	s_waitcnt vmcnt(11) lgkmcnt(0)
	v_mov_b64_e32 v[70:71], v[58:59]
	s_waitcnt vmcnt(10)
	v_mov_b64_e32 v[66:67], v[62:63]
	v_lshl_add_u64 v[110:111], v[110:111], 0, 64
	v_lshl_add_u64 v[112:113], v[112:113], 0, s[18:19]
	v_lshl_add_u64 v[114:115], v[114:115], 0, s[16:17]
	s_andn2_b64 vcc, exec, s[22:23]
	v_mov_b64_e32 v[92:93], v[32:33]
	v_mov_b64_e32 v[88:89], v[36:37]
	v_mov_b64_e32 v[84:85], v[40:41]
	v_mov_b64_e32 v[80:81], v[44:45]
	v_mov_b64_e32 v[76:77], v[48:49]
	v_mov_b64_e32 v[72:73], v[52:53]
	v_mov_b64_e32 v[68:69], v[56:57]
	v_mov_b64_e32 v[64:65], v[60:61]
	s_mov_b32 s14, s37
	s_cbranch_vccz .LBB0_201
; __device__ __forceinline__ void phase1(const Params& p, LAS unsigned char* lds, int tid, int lane, int wave) {
;     ...
;     for (int row = r0; row < r1; row += 2) {
;         const int b = row >> 11;
;         if (b != bcur) { bcur = b; const float* mb = mod + b * NMOD;
; #pragma unroll
;             for (int j = 0; j < 4; ++j) { const int col = 4 * lane + 256 * j; gmv[j] = *(const f32x4*)(p.n1g + col) * (*(const f32x4*)(mb + 1024 + col) + 1.f); shv[j] = *(const f32x4*)(mb + col); } }
;         f32x4 v[2][4]; float ss[2];
; #pragma unroll
;         for (int q = 0; q < 2; ++q) { ss[q] = 0.f;
; #pragma unroll
;             for (int j = 0; j < 4; ++j) { v[q][j] = vn[q][j]; ss[q] += (v[q][j].x * v[q][j].x + v[q][j].y * v[q][j].y) + (v[q][j].z * v[q][j].z + v[q][j].w * v[q][j].w); } }
;         if (row + 2 < r1) {
; #pragma unroll
;             for (int q = 0; q < 2; ++q)
; #pragma unroll
;                 for (int j = 0; j < 4; ++j) vn[q][j] = __builtin_nontemporal_load((const f32x4*)(p.x + (size_t)ROW2(row + 2, q) * D_ + 4 * lane + 256 * j)); }
; #pragma unroll
;         for (int q = 0; q < 2; ++q) ss[q] = xsum12(ss[q]);
; #pragma unroll
;         for (int o = 4; o < 64; o <<= 1) { ss[0] += __shfl_xor(ss[0], o); ss[1] += __shfl_xor(ss[1], o); }
.LBB0_195:
	s_ashr_i32 s15, s14, 11
	s_cmp_eq_u32 s15, s40
	s_cbranch_scc1 .LBB0_197
	s_mul_i32 s22, s15, 0x1800
	s_ashr_i32 s23, s22, 31
	s_lshl_b64 s[22:23], s[22:23], 2
	s_add_u32 s22, s30, s22
	s_addc_u32 s23, s31, s23
	s_add_u32 s34, s22, 0x1000
	s_addc_u32 s35, s23, 0
	global_load_dwordx4 v[16:19], v99, s[34:35]
	global_load_dwordx4 v[20:23], v124, s[34:35]
	global_load_dwordx4 v[24:27], v125, s[34:35]
	global_load_dwordx4 v[28:31], v126, s[34:35]
	global_load_dwordx4 v[32:35], v[104:105], off
	global_load_dwordx4 v[36:39], v[104:105], off offset:1024
	global_load_dwordx4 v[40:43], v[104:105], off offset:2048
	global_load_dwordx4 v[44:47], v[104:105], off offset:3072
	global_load_dwordx4 v[0:3], v99, s[22:23]
	global_load_dwordx4 v[4:7], v99, s[22:23] offset:1024
	global_load_dwordx4 v[8:11], v99, s[22:23] offset:2048
	global_load_dwordx4 v[12:15], v99, s[22:23] offset:3072
	s_mov_b32 s40, s15
	s_waitcnt vmcnt(11)
	v_pk_add_f32 v[18:19], v[18:19], 1.0 op_sel_hi:[1,0]
	v_pk_add_f32 v[16:17], v[16:17], 1.0 op_sel_hi:[1,0]
	s_waitcnt vmcnt(10)
	v_pk_add_f32 v[22:23], v[22:23], 1.0 op_sel_hi:[1,0]
	v_pk_add_f32 v[20:21], v[20:21], 1.0 op_sel_hi:[1,0]
	s_waitcnt vmcnt(9)
	v_pk_add_f32 v[26:27], v[26:27], 1.0 op_sel_hi:[1,0]
	v_pk_add_f32 v[24:25], v[24:25], 1.0 op_sel_hi:[1,0]
	s_waitcnt vmcnt(8)
	v_pk_add_f32 v[30:31], v[30:31], 1.0 op_sel_hi:[1,0]
	v_pk_add_f32 v[28:29], v[28:29], 1.0 op_sel_hi:[1,0]
	s_waitcnt vmcnt(7)
	v_pk_mul_f32 v[18:19], v[34:35], v[18:19]
	v_pk_mul_f32 v[16:17], v[32:33], v[16:17]
	s_waitcnt vmcnt(6)
	v_pk_mul_f32 v[22:23], v[38:39], v[22:23]
	v_pk_mul_f32 v[20:21], v[36:37], v[20:21]
	s_waitcnt vmcnt(5)
	v_pk_mul_f32 v[26:27], v[42:43], v[26:27]
	v_pk_mul_f32 v[24:25], v[40:41], v[24:25]
	s_waitcnt vmcnt(4)
	v_pk_mul_f32 v[30:31], v[46:47], v[30:31]
	v_pk_mul_f32 v[28:29], v[44:45], v[28:29]
	s_waitcnt vmcnt(0)
.LBB0_197:
	s_add_i32 s37, s14, 2
	s_cmp_ge_i32 s37, s4
	s_cselect_b64 s[22:23], -1, 0
	v_mov_b64_e32 v[32:33], v[92:93]
	v_mov_b64_e32 v[36:37], v[88:89]
	v_mov_b64_e32 v[40:41], v[84:85]
	v_mov_b64_e32 v[44:45], v[80:81]
	v_mov_b64_e32 v[48:49], v[76:77]
	v_mov_b64_e32 v[52:53], v[72:73]
	v_mov_b64_e32 v[56:57], v[68:69]
	v_mov_b64_e32 v[60:61], v[64:65]
	s_and_b64 vcc, exec, s[22:23]
	v_mov_b64_e32 v[34:35], v[94:95]
	v_mov_b64_e32 v[38:39], v[90:91]
	v_mov_b64_e32 v[42:43], v[86:87]
	v_mov_b64_e32 v[46:47], v[82:83]
	v_mov_b64_e32 v[50:51], v[78:79]
	v_mov_b64_e32 v[54:55], v[74:75]
	v_mov_b64_e32 v[58:59], v[70:71]
	v_mov_b64_e32 v[62:63], v[66:67]
	s_cbranch_vccnz .LBB0_199
	s_add_i32 s0, s14, 3
	s_cmp_lt_i32 s0, s4
	s_cselect_b32 s34, s0, s37
	s_ashr_i32 s35, s34, 31
	s_lshl_b64 s[34:35], s[34:35], 12
	v_lshl_add_u64 v[60:61], v[100:101], 0, s[34:35]
	global_load_dwordx4 v[32:35], v[114:115], off nt
	global_load_dwordx4 v[36:39], v[114:115], off offset:1024 nt
	global_load_dwordx4 v[40:43], v[114:115], off offset:2048 nt
	global_load_dwordx4 v[44:47], v[114:115], off offset:3072 nt
	global_load_dwordx4 v[48:51], v[60:61], off nt
	global_load_dwordx4 v[52:55], v[60:61], off offset:1024 nt
	global_load_dwordx4 v[56:59], v[60:61], off offset:2048 nt
	s_nop 0
	global_load_dwordx4 v[60:63], v[60:61], off offset:3072 nt
.LBB0_199:
	v_mov_b32_e32 v120, v77
	v_mov_b32_e32 v121, v93
	v_mov_b32_e32 v118, v76
	v_mov_b32_e32 v119, v92
	v_pk_mul_f32 v[120:121], v[120:121], v[120:121]
	v_mov_b32_e32 v128, v79
	v_mov_b32_e32 v129, v95
	v_pk_fma_f32 v[118:119], v[118:119], v[118:119], v[120:121]
	v_mov_b32_e32 v120, v78
	v_mov_b32_e32 v121, v94
	v_pk_mul_f32 v[128:129], v[128:129], v[128:129]
	v_mov_b32_e32 v130, v75
	v_pk_fma_f32 v[120:121], v[120:121], v[120:121], v[128:129]
	v_mov_b32_e32 v128, v73
	v_mov_b32_e32 v129, v89
	v_pk_add_f32 v[118:119], v[118:119], v[120:121]
	v_mov_b32_e32 v120, v72
	v_mov_b32_e32 v121, v88
	v_pk_mul_f32 v[128:129], v[128:129], v[128:129]
	v_mov_b32_e32 v131, v91
	v_pk_fma_f32 v[120:121], v[120:121], v[120:121], v[128:129]
	v_mov_b32_e32 v128, v74
	v_mov_b32_e32 v129, v90
	v_pk_mul_f32 v[130:131], v[130:131], v[130:131]
	v_mov_b32_e32 v132, v71
	v_pk_fma_f32 v[128:129], v[128:129], v[128:129], v[130:131]
	v_mov_b32_e32 v130, v69
	v_mov_b32_e32 v131, v85
	v_pk_add_f32 v[120:121], v[120:121], v[128:129]
	v_mov_b32_e32 v128, v68
	v_mov_b32_e32 v129, v84
	v_pk_mul_f32 v[130:131], v[130:131], v[130:131]
	v_mov_b32_e32 v133, v87
	v_pk_fma_f32 v[128:129], v[128:129], v[128:129], v[130:131]
	v_mov_b32_e32 v130, v70
	v_mov_b32_e32 v131, v86
	v_pk_mul_f32 v[132:133], v[132:133], v[132:133]
	v_mov_b32_e32 v134, v65
	v_pk_fma_f32 v[130:131], v[130:131], v[130:131], v[132:133]
	v_mov_b32_e32 v135, v81
	v_mov_b32_e32 v138, v67
	v_mov_b32_e32 v139, v83
	v_mov_b32_e32 v132, v64
	v_mov_b32_e32 v133, v80
	v_pk_mul_f32 v[134:135], v[134:135], v[134:135]
	v_mov_b32_e32 v136, v66
	v_mov_b32_e32 v137, v82
	v_pk_mul_f32 v[138:139], v[138:139], v[138:139]
	v_pk_add_f32 v[118:119], v[118:119], v[120:121]
	v_pk_add_f32 v[120:121], v[128:129], v[130:131]
	v_pk_fma_f32 v[128:129], v[136:137], v[136:137], v[138:139]
	v_pk_add_f32 v[118:119], v[118:119], v[120:121]
	v_pk_fma_f32 v[120:121], v[132:133], v[132:133], v[134:135]
	s_add_i32 s0, s14, 1
	v_pk_add_f32 v[120:121], v[120:121], v[128:129]
	s_cmp_lt_i32 s0, s4
	v_pk_add_f32 v[118:119], v[118:119], v[120:121]
	s_cselect_b32 s14, s0, s14
	s_ashr_i32 s15, s14, 31
	v_mov_b32_dpp v121, v119 quad_perm:[1,0,3,2] row_mask:0xf bank_mask:0xf bound_ctrl:1
	v_mov_b32_dpp v120, v118 quad_perm:[1,0,3,2] row_mask:0xf bank_mask:0xf bound_ctrl:1
	v_pk_add_f32 v[118:119], v[118:119], v[120:121]
	s_lshl_b64 s[34:35], s[14:15], 11
	s_nop 0
	v_mov_b32_dpp v121, v119 quad_perm:[2,3,0,1] row_mask:0xf bank_mask:0xf bound_ctrl:1
	v_mov_b32_dpp v120, v118 quad_perm:[2,3,0,1] row_mask:0xf bank_mask:0xf bound_ctrl:1
	v_pk_add_f32 v[118:119], v[118:119], v[120:121]
	ds_bpermute_b32 v121, v97, v119
	ds_bpermute_b32 v120, v97, v118
	s_waitcnt lgkmcnt(0)
; #define LAS __attribute__((address_space(3)))
; __device__ __forceinline__ unsigned pk2(float lo, float hi) { return pg8::cvt_pk_bf16(lo, hi); }
; __device__ __forceinline__ void phase1(const Params& p, LAS unsigned char* lds, int tid, int lane, int wave) {
;     ...
;         for (int o = 4; o < 64; o <<= 1) { ss[0] += __shfl_xor(ss[0], o); ss[1] += __shfl_xor(ss[1], o); }
; #pragma unroll
;         for (int q = 0; q < 2; ++q) { const float rstd = rsqrtf(ss[q] * (1.f / D_) + EPS); const int rq = ROW2(row, q);
; #pragma unroll
;             for (int j = 0; j < 4; ++j) { const int col = 4 * lane + 256 * j;
;                 v[q][j] = (v[q][j] * rstd) * gmv[j] + shv[j];
;                 u32x2 w; w.x = pk2(v[q][j].x, v[q][j].y); w.y = pk2(v[q][j].z, v[q][j].w);
;                 *(u32x2*)(hb + (size_t)rq * D_ + col) = w; } }
;         float f[2][8];
; #pragma unroll
;         for (int h = 0; h < 8; ++h) { float s0 = 0.f, s1 = 0.f;
; #pragma unroll
;             for (int j = 0; j < 4; ++j) { const f32x4 w = *(const LAS f32x4*)(wf + h * 1024 + 4 * lane + 256 * j);
;                 s0 += (v[0][j].x * w.x + v[0][j].y * w.y) + (v[0][j].z * w.z + v[0][j].w * w.w); s1 += (v[1][j].x * w.x + v[1][j].y * w.y) + (v[1][j].z * w.z + v[1][j].w * w.w); }
	v_pk_add_f32 v[118:119], v[118:119], v[120:121]
	ds_bpermute_b32 v121, v117, v119
	ds_bpermute_b32 v120, v117, v118
	s_waitcnt lgkmcnt(0)
	v_pk_add_f32 v[118:119], v[118:119], v[120:121]
	ds_bpermute_b32 v121, v122, v119
	ds_bpermute_b32 v120, v122, v118
	s_waitcnt lgkmcnt(0)
	v_pk_add_f32 v[118:119], v[118:119], v[120:121]
	ds_bpermute_b32 v121, v123, v119
	ds_bpermute_b32 v120, v123, v118
	s_waitcnt lgkmcnt(0)
	v_pk_add_f32 v[118:119], v[118:119], v[120:121]
	s_nop 0
	v_pk_fma_f32 v[118:119], v[118:119], s[20:21], v[116:117] op_sel_hi:[1,0,0]
	s_nop 0
	v_mul_f32_e32 v120, 0x4b800000, v119
	v_cmp_gt_f32_e32 vcc, s5, v119
	s_nop 1
	v_cndmask_b32_e32 v119, v119, v120, vcc
	v_rsq_f32_e32 v119, v119
	v_lshl_add_u64 v[120:121], s[30:31], 0, v[112:113]
	v_mul_f32_e32 v128, 0x45800000, v119
	v_cndmask_b32_e32 v128, v119, v128, vcc
	v_pk_mul_f32 v[130:131], v[92:93], v[128:129] op_sel_hi:[1,0]
	v_pk_mul_f32 v[92:93], v[94:95], v[128:129] op_sel_hi:[1,0]
	v_add_co_u32_e32 v120, vcc, s21, v120
	v_pk_fma_f32 v[92:93], v[18:19], v[92:93], v[2:3]
	v_pk_fma_f32 v[94:95], v[16:17], v[130:131], v[0:1]
	v_addc_co_u32_e32 v121, vcc, 0, v121, vcc
	v_cvt_pk_bf16_f32 v130, v94, v95
	v_cvt_pk_bf16_f32 v131, v92, v93
	global_store_dwordx2 v[120:121], v[130:131], off sc1
	v_pk_mul_f32 v[130:131], v[88:89], v[128:129] op_sel_hi:[1,0]
	v_pk_mul_f32 v[88:89], v[90:91], v[128:129] op_sel_hi:[1,0]
	v_pk_fma_f32 v[90:91], v[20:21], v[130:131], v[4:5]
	v_pk_fma_f32 v[88:89], v[22:23], v[88:89], v[6:7]
	v_cvt_pk_bf16_f32 v130, v90, v91
	v_mul_f32_e32 v119, 0x4b800000, v118
	v_cvt_pk_bf16_f32 v131, v88, v89
	global_store_dwordx2 v[120:121], v[130:131], off offset:512 sc1
	v_pk_mul_f32 v[130:131], v[84:85], v[128:129] op_sel_hi:[1,0]
	v_pk_mul_f32 v[84:85], v[86:87], v[128:129] op_sel_hi:[1,0]
	v_cmp_gt_f32_e32 vcc, s5, v118
	v_pk_fma_f32 v[84:85], v[26:27], v[84:85], v[10:11]
	v_pk_fma_f32 v[86:87], v[24:25], v[130:131], v[8:9]
	v_cndmask_b32_e32 v118, v118, v119, vcc
	v_cvt_pk_bf16_f32 v130, v86, v87
	v_cvt_pk_bf16_f32 v131, v84, v85
	global_store_dwordx2 v[120:121], v[130:131], off offset:1024 sc1
	v_pk_mul_f32 v[130:131], v[80:81], v[128:129] op_sel_hi:[1,0]
	v_pk_mul_f32 v[80:81], v[82:83], v[128:129] op_sel_hi:[1,0]
	v_rsq_f32_e32 v128, v118
	v_pk_fma_f32 v[82:83], v[28:29], v[130:131], v[12:13]
	v_pk_fma_f32 v[80:81], v[30:31], v[80:81], v[14:15]
	v_cvt_pk_bf16_f32 v118, v82, v83
	s_nop 0
	v_cvt_pk_bf16_f32 v119, v80, v81
	global_store_dwordx2 v[120:121], v[118:119], off offset:1536 sc1
	v_mul_f32_e32 v118, 0x45800000, v128
	v_cndmask_b32_e32 v128, v128, v118, vcc
	v_pk_mul_f32 v[76:77], v[76:77], v[128:129] op_sel_hi:[1,0]
	v_pk_mul_f32 v[78:79], v[78:79], v[128:129] op_sel_hi:[1,0]
	v_pk_fma_f32 v[120:121], v[16:17], v[76:77], v[0:1]
	v_pk_fma_f32 v[78:79], v[18:19], v[78:79], v[2:3]
	v_cvt_pk_bf16_f32 v118, v120, v121
	v_lshl_add_u64 v[76:77], v[108:109], 0, s[34:35]
	v_cvt_pk_bf16_f32 v119, v78, v79
	v_pk_mul_f32 v[72:73], v[72:73], v[128:129] op_sel_hi:[1,0]
	v_pk_mul_f32 v[74:75], v[74:75], v[128:129] op_sel_hi:[1,0]
	global_store_dwordx2 v[76:77], v[118:119], off sc1
	v_pk_fma_f32 v[74:75], v[22:23], v[74:75], v[6:7]
	v_pk_fma_f32 v[118:119], v[20:21], v[72:73], v[4:5]
	v_pk_mul_f32 v[64:65], v[64:65], v[128:129] op_sel_hi:[1,0]
	v_cvt_pk_bf16_f32 v72, v118, v119
	v_cvt_pk_bf16_f32 v73, v74, v75
	global_store_dwordx2 v[76:77], v[72:73], off offset:512 sc1
	v_pk_mul_f32 v[72:73], v[68:69], v[128:129] op_sel_hi:[1,0]
	v_pk_mul_f32 v[68:69], v[70:71], v[128:129] op_sel_hi:[1,0]
	v_pk_fma_f32 v[72:73], v[24:25], v[72:73], v[8:9]
	v_pk_fma_f32 v[68:69], v[26:27], v[68:69], v[10:11]
	v_cvt_pk_bf16_f32 v70, v72, v73
	v_pk_mul_f32 v[66:67], v[66:67], v[128:129] op_sel_hi:[1,0]
	v_cvt_pk_bf16_f32 v71, v68, v69
	v_add_u32_e32 v128, 0, v98
	global_store_dwordx2 v[76:77], v[70:71], off offset:1024 sc1
	v_pk_fma_f32 v[66:67], v[30:31], v[66:67], v[14:15]
	v_pk_fma_f32 v[70:71], v[28:29], v[64:65], v[12:13]
	s_nop 0
	v_cvt_pk_bf16_f32 v64, v70, v71
	v_cvt_pk_bf16_f32 v65, v66, v67
	ds_read_b128 v[130:133], v128
	ds_read_b128 v[134:137], v128 offset:1024
	global_store_dwordx2 v[76:77], v[64:65], off offset:1536 sc1
	s_waitcnt lgkmcnt(1)
	v_mul_f32_e32 v129, v95, v131
	v_mul_f32_e32 v131, v121, v131
	v_fmac_f32_e32 v129, v94, v130
	v_fmac_f32_e32 v131, v120, v130
	v_mul_f32_e32 v130, v79, v133
	v_mul_f32_e32 v138, v93, v133
	v_fmac_f32_e32 v130, v78, v132
	v_fmac_f32_e32 v138, v92, v132
	v_add_f32_e32 v130, v131, v130
	v_add_f32_e32 v129, v129, v138
	v_add_f32_e32 v138, 0, v130
	s_waitcnt lgkmcnt(0)
	v_mul_f32_e32 v130, v91, v135
	v_mul_f32_e32 v131, v89, v137
	v_fmac_f32_e32 v130, v90, v134
	v_fmac_f32_e32 v131, v88, v136
	v_add_f32_e32 v129, 0, v129
	v_add_f32_e32 v130, v130, v131
	v_mul_f32_e32 v135, v119, v135
	v_add_f32_e32 v129, v129, v130
	v_fmac_f32_e32 v135, v118, v134
	v_mul_f32_e32 v134, v75, v137
	ds_read_b128 v[130:133], v128 offset:2048
	v_fmac_f32_e32 v134, v74, v136
	v_add_f32_e32 v134, v135, v134
	v_add_f32_e32 v138, v138, v134
	ds_read_b128 v[134:137], v128 offset:3072
	s_waitcnt lgkmcnt(1)
	v_mul_f32_e32 v139, v87, v131
	v_mul_f32_e32 v131, v73, v131
	v_fmac_f32_e32 v139, v86, v130
	v_fmac_f32_e32 v131, v72, v130
	v_mul_f32_e32 v130, v69, v133
	v_mul_f32_e32 v140, v85, v133
	v_fmac_f32_e32 v130, v68, v132
	v_fmac_f32_e32 v140, v84, v132
	v_add_f32_e32 v130, v131, v130
	s_waitcnt lgkmcnt(0)
; #define LAS __attribute__((address_space(3)))
; __device__ __forceinline__ void phase1(const Params& p, LAS unsigned char* lds, int tid, int lane, int wave) {
;     ...
;         for (int h = 0; h < 8; ++h) { float s0 = 0.f, s1 = 0.f;
; #pragma unroll
;             for (int j = 0; j < 4; ++j) { const f32x4 w = *(const LAS f32x4*)(wf + h * 1024 + 4 * lane + 256 * j);
;                 s0 += (v[0][j].x * w.x + v[0][j].y * w.y) + (v[0][j].z * w.z + v[0][j].w * w.w); s1 += (v[1][j].x * w.x + v[1][j].y * w.y) + (v[1][j].z * w.z + v[1][j].w * w.w); }
;             f[0][h] = s0; f[1][h] = s1; }
	v_mul_f32_e32 v131, v83, v135
	v_mul_f32_e32 v132, v81, v137
	v_add_f32_e32 v139, v139, v140
	v_fmac_f32_e32 v131, v82, v134
	v_fmac_f32_e32 v132, v80, v136
	v_add_f32_e32 v129, v129, v139
	v_add_f32_e32 v131, v131, v132
	v_add_f32_e32 v129, v129, v131
	v_mul_f32_e32 v131, v71, v135
	v_fmac_f32_e32 v131, v70, v134
	ds_read_b128 v[132:135], v128 offset:4096
	v_mul_f32_e32 v137, v67, v137
	v_fmac_f32_e32 v137, v66, v136
	v_add_f32_e32 v130, v138, v130
	v_add_f32_e32 v131, v131, v137
	ds_read_b128 v[136:139], v128 offset:5120
	v_add_f32_e32 v130, v130, v131
	s_waitcnt lgkmcnt(1)
	v_mul_f32_e32 v131, v95, v133
	v_mul_f32_e32 v133, v121, v133
	v_fmac_f32_e32 v131, v94, v132
	v_fmac_f32_e32 v133, v120, v132
	v_mul_f32_e32 v132, v79, v135
	v_mul_f32_e32 v140, v93, v135
	v_fmac_f32_e32 v132, v78, v134
	v_fmac_f32_e32 v140, v92, v134
	v_add_f32_e32 v132, v133, v132
	v_add_f32_e32 v131, v131, v140
	v_add_f32_e32 v140, 0, v132
	s_waitcnt lgkmcnt(0)
	v_mul_f32_e32 v132, v91, v137
	v_mul_f32_e32 v133, v89, v139
	v_fmac_f32_e32 v132, v90, v136
	v_fmac_f32_e32 v133, v88, v138
	v_add_f32_e32 v131, 0, v131
	v_add_f32_e32 v132, v132, v133
	v_mul_f32_e32 v137, v119, v137
	v_add_f32_e32 v131, v131, v132
	v_fmac_f32_e32 v137, v118, v136
	v_mul_f32_e32 v136, v75, v139
	ds_read_b128 v[132:135], v128 offset:6144
	v_fmac_f32_e32 v136, v74, v138
	v_add_f32_e32 v136, v137, v136
	v_add_f32_e32 v140, v140, v136
	ds_read_b128 v[136:139], v128 offset:7168
	s_waitcnt lgkmcnt(1)
	v_mul_f32_e32 v141, v87, v133
	v_mul_f32_e32 v133, v73, v133
	v_fmac_f32_e32 v141, v86, v132
	v_fmac_f32_e32 v133, v72, v132
	v_mul_f32_e32 v132, v69, v135
	v_mul_f32_e32 v142, v85, v135
	v_fmac_f32_e32 v132, v68, v134
	v_fmac_f32_e32 v142, v84, v134
	v_add_f32_e32 v132, v133, v132
	s_waitcnt lgkmcnt(0)
	v_mul_f32_e32 v133, v83, v137
	v_mul_f32_e32 v134, v81, v139
	v_add_f32_e32 v141, v141, v142
	v_fmac_f32_e32 v133, v82, v136
	v_fmac_f32_e32 v134, v80, v138
	v_add_f32_e32 v131, v131, v141
	v_add_f32_e32 v133, v133, v134
	v_add_f32_e32 v131, v131, v133
	v_mul_f32_e32 v133, v71, v137
	v_fmac_f32_e32 v133, v70, v136
	ds_read_b128 v[134:137], v128 offset:8192
	v_mul_f32_e32 v139, v67, v139
	v_fmac_f32_e32 v139, v66, v138
	v_add_f32_e32 v132, v140, v132
	v_add_f32_e32 v133, v133, v139
	ds_read_b128 v[138:141], v128 offset:9216
	v_add_f32_e32 v132, v132, v133
	s_waitcnt lgkmcnt(1)
	v_mul_f32_e32 v133, v95, v135
	v_mul_f32_e32 v135, v121, v135
	v_fmac_f32_e32 v133, v94, v134
	v_fmac_f32_e32 v135, v120, v134
	v_mul_f32_e32 v134, v79, v137
	v_mul_f32_e32 v142, v93, v137
	v_fmac_f32_e32 v134, v78, v136
	v_fmac_f32_e32 v142, v92, v136
	v_add_f32_e32 v134, v135, v134
	v_add_f32_e32 v133, v133, v142
	v_add_f32_e32 v142, 0, v134
	s_waitcnt lgkmcnt(0)
	v_mul_f32_e32 v134, v91, v139
	v_mul_f32_e32 v135, v89, v141
	v_fmac_f32_e32 v134, v90, v138
	v_fmac_f32_e32 v135, v88, v140
	v_add_f32_e32 v133, 0, v133
	v_add_f32_e32 v134, v134, v135
	v_mul_f32_e32 v139, v119, v139
	v_add_f32_e32 v133, v133, v134
	v_fmac_f32_e32 v139, v118, v138
	v_mul_f32_e32 v138, v75, v141
	ds_read_b128 v[134:137], v128 offset:10240
	v_fmac_f32_e32 v138, v74, v140
	v_add_f32_e32 v138, v139, v138
	v_add_f32_e32 v142, v142, v138
	ds_read_b128 v[138:141], v128 offset:11264
	s_waitcnt lgkmcnt(1)
	v_mul_f32_e32 v143, v87, v135
	v_mul_f32_e32 v135, v73, v135
	v_fmac_f32_e32 v143, v86, v134
	v_fmac_f32_e32 v135, v72, v134
	v_mul_f32_e32 v134, v69, v137
	v_mul_f32_e32 v144, v85, v137
	v_fmac_f32_e32 v134, v68, v136
	v_fmac_f32_e32 v144, v84, v136
	v_add_f32_e32 v134, v135, v134
	s_waitcnt lgkmcnt(0)
	v_mul_f32_e32 v135, v83, v139
	v_mul_f32_e32 v136, v81, v141
	v_add_f32_e32 v143, v143, v144
	v_fmac_f32_e32 v135, v82, v138
	v_fmac_f32_e32 v136, v80, v140
	v_add_f32_e32 v133, v133, v143
	v_add_f32_e32 v135, v135, v136
	v_add_f32_e32 v133, v133, v135
	v_mul_f32_e32 v135, v71, v139
	v_fmac_f32_e32 v135, v70, v138
	ds_read_b128 v[136:139], v128 offset:12288
	v_mul_f32_e32 v141, v67, v141
	v_fmac_f32_e32 v141, v66, v140
	v_add_f32_e32 v134, v142, v134
	v_add_f32_e32 v135, v135, v141
	ds_read_b128 v[140:143], v128 offset:13312
	v_add_f32_e32 v134, v134, v135
	s_waitcnt lgkmcnt(1)
	v_mul_f32_e32 v135, v95, v137
	v_mul_f32_e32 v137, v121, v137
	v_fmac_f32_e32 v135, v94, v136
	v_fmac_f32_e32 v137, v120, v136
	v_mul_f32_e32 v136, v79, v139
	v_mul_f32_e32 v144, v93, v139
	v_fmac_f32_e32 v136, v78, v138
	v_fmac_f32_e32 v144, v92, v138
	v_add_f32_e32 v136, v137, v136
	v_add_f32_e32 v135, v135, v144
	v_add_f32_e32 v144, 0, v136
	s_waitcnt lgkmcnt(0)
	v_mul_f32_e32 v136, v91, v141
	v_mul_f32_e32 v137, v89, v143
	v_fmac_f32_e32 v136, v90, v140
	v_fmac_f32_e32 v137, v88, v142
	v_add_f32_e32 v135, 0, v135
	v_add_f32_e32 v136, v136, v137
	v_add_f32_e32 v135, v135, v136
	v_mul_f32_e32 v141, v119, v141
	ds_read_b128 v[136:139], v128 offset:14336
	v_fmac_f32_e32 v141, v118, v140
	v_mul_f32_e32 v140, v75, v143
	v_fmac_f32_e32 v140, v74, v142
	v_add_f32_e32 v140, v141, v140
	v_add_f32_e32 v144, v144, v140
	ds_read_b128 v[140:143], v128 offset:15360
	s_waitcnt lgkmcnt(1)
	v_mul_f32_e32 v145, v87, v137
	v_mul_f32_e32 v137, v73, v137
	v_fmac_f32_e32 v145, v86, v136
	v_fmac_f32_e32 v137, v72, v136
	v_mul_f32_e32 v136, v69, v139
	v_fmac_f32_e32 v136, v68, v138
	v_mul_f32_e32 v146, v85, v139
	v_add_f32_e32 v136, v137, v136
	v_fmac_f32_e32 v146, v84, v138
	v_add_f32_e32 v144, v144, v136
	s_waitcnt lgkmcnt(0)
; #define LAS __attribute__((address_space(3)))
; __device__ __forceinline__ void phase1(const Params& p, LAS unsigned char* lds, int tid, int lane, int wave) {
;     ...
;         for (int h = 0; h < 8; ++h) { float s0 = 0.f, s1 = 0.f;
; #pragma unroll
;             for (int j = 0; j < 4; ++j) { const f32x4 w = *(const LAS f32x4*)(wf + h * 1024 + 4 * lane + 256 * j);
;                 s0 += (v[0][j].x * w.x + v[0][j].y * w.y) + (v[0][j].z * w.z + v[0][j].w * w.w); s1 += (v[1][j].x * w.x + v[1][j].y * w.y) + (v[1][j].z * w.z + v[1][j].w * w.w); }
;             f[0][h] = s0; f[1][h] = s1; }
	v_mul_f32_e32 v136, v83, v141
	v_mul_f32_e32 v137, v81, v143
	v_add_f32_e32 v145, v145, v146
	v_fmac_f32_e32 v136, v82, v140
	v_fmac_f32_e32 v137, v80, v142
	v_add_f32_e32 v135, v135, v145
	v_add_f32_e32 v136, v136, v137
	v_add_f32_e32 v135, v135, v136
	v_mul_f32_e32 v141, v71, v141
	ds_read_b128 v[136:139], v128 offset:16384
	v_fmac_f32_e32 v141, v70, v140
	v_mul_f32_e32 v140, v67, v143
	v_fmac_f32_e32 v140, v66, v142
	v_add_f32_e32 v140, v141, v140
	v_add_f32_e32 v144, v144, v140
	ds_read_b128 v[140:143], v128 offset:17408
	s_waitcnt lgkmcnt(1)
	v_mul_f32_e32 v145, v95, v137
	v_mul_f32_e32 v137, v121, v137
	v_fmac_f32_e32 v145, v94, v136
	v_fmac_f32_e32 v137, v120, v136
	v_mul_f32_e32 v136, v79, v139
	v_mul_f32_e32 v146, v93, v139
	v_fmac_f32_e32 v136, v78, v138
	v_fmac_f32_e32 v146, v92, v138
	v_add_f32_e32 v136, v137, v136
	v_add_f32_e32 v145, v145, v146
	v_add_f32_e32 v146, 0, v136
	s_waitcnt lgkmcnt(0)
	v_mul_f32_e32 v136, v91, v141
	v_mul_f32_e32 v137, v89, v143
	v_fmac_f32_e32 v136, v90, v140
	v_fmac_f32_e32 v137, v88, v142
	v_add_f32_e32 v145, 0, v145
	v_add_f32_e32 v136, v136, v137
	v_add_f32_e32 v145, v145, v136
	v_mul_f32_e32 v141, v119, v141
	ds_read_b128 v[136:139], v128 offset:18432
	v_fmac_f32_e32 v141, v118, v140
	v_mul_f32_e32 v140, v75, v143
	v_fmac_f32_e32 v140, v74, v142
	v_add_f32_e32 v140, v141, v140
	v_add_f32_e32 v146, v146, v140
	ds_read_b128 v[140:143], v128 offset:19456
	s_waitcnt lgkmcnt(1)
	v_mul_f32_e32 v147, v87, v137
	v_mul_f32_e32 v137, v73, v137
	v_fmac_f32_e32 v147, v86, v136
	v_fmac_f32_e32 v137, v72, v136
	v_mul_f32_e32 v136, v69, v139
	v_fmac_f32_e32 v136, v68, v138
	v_mul_f32_e32 v148, v85, v139
	v_add_f32_e32 v136, v137, v136
	v_fmac_f32_e32 v148, v84, v138
	v_add_f32_e32 v146, v146, v136
	s_waitcnt lgkmcnt(0)
	v_mul_f32_e32 v136, v83, v141
	v_mul_f32_e32 v137, v81, v143
	v_add_f32_e32 v147, v147, v148
	v_fmac_f32_e32 v136, v82, v140
	v_fmac_f32_e32 v137, v80, v142
	v_add_f32_e32 v145, v145, v147
	v_add_f32_e32 v136, v136, v137
	v_add_f32_e32 v145, v145, v136
	v_mul_f32_e32 v141, v71, v141
	ds_read_b128 v[136:139], v128 offset:20480
	v_fmac_f32_e32 v141, v70, v140
	v_mul_f32_e32 v140, v67, v143
	v_fmac_f32_e32 v140, v66, v142
	v_add_f32_e32 v140, v141, v140
	v_add_f32_e32 v146, v146, v140
	ds_read_b128 v[140:143], v128 offset:21504
	s_waitcnt lgkmcnt(1)
	v_mul_f32_e32 v147, v95, v137
	v_mul_f32_e32 v137, v121, v137
	v_fmac_f32_e32 v147, v94, v136
	v_fmac_f32_e32 v137, v120, v136
	v_mul_f32_e32 v136, v79, v139
	v_mul_f32_e32 v148, v93, v139
	v_fmac_f32_e32 v136, v78, v138
	v_fmac_f32_e32 v148, v92, v138
	v_add_f32_e32 v136, v137, v136
	v_add_f32_e32 v147, v147, v148
	v_add_f32_e32 v148, 0, v136
	s_waitcnt lgkmcnt(0)
	v_mul_f32_e32 v136, v91, v141
	v_mul_f32_e32 v137, v89, v143
	v_fmac_f32_e32 v136, v90, v140
	v_fmac_f32_e32 v137, v88, v142
	v_add_f32_e32 v147, 0, v147
	v_add_f32_e32 v136, v136, v137
	v_add_f32_e32 v147, v147, v136
	v_mul_f32_e32 v141, v119, v141
	ds_read_b128 v[136:139], v128 offset:22528
	v_fmac_f32_e32 v141, v118, v140
	v_mul_f32_e32 v140, v75, v143
	v_fmac_f32_e32 v140, v74, v142
	v_add_f32_e32 v140, v141, v140
	v_add_f32_e32 v148, v148, v140
	ds_read_b128 v[140:143], v128 offset:23552
	s_waitcnt lgkmcnt(1)
	v_mul_f32_e32 v149, v87, v137
	v_mul_f32_e32 v137, v73, v137
	v_fmac_f32_e32 v149, v86, v136
	v_fmac_f32_e32 v137, v72, v136
	v_mul_f32_e32 v136, v69, v139
	v_fmac_f32_e32 v136, v68, v138
	v_mul_f32_e32 v150, v85, v139
	v_add_f32_e32 v136, v137, v136
	v_fmac_f32_e32 v150, v84, v138
	v_add_f32_e32 v148, v148, v136
	s_waitcnt lgkmcnt(0)
	v_mul_f32_e32 v136, v83, v141
	v_mul_f32_e32 v137, v81, v143
	v_add_f32_e32 v149, v149, v150
	v_fmac_f32_e32 v136, v82, v140
	v_fmac_f32_e32 v137, v80, v142
	v_add_f32_e32 v147, v147, v149
	v_add_f32_e32 v136, v136, v137
	v_add_f32_e32 v147, v147, v136
	v_mul_f32_e32 v141, v71, v141
	ds_read_b128 v[136:139], v128 offset:24576
	v_fmac_f32_e32 v141, v70, v140
	v_mul_f32_e32 v140, v67, v143
	v_fmac_f32_e32 v140, v66, v142
	v_add_f32_e32 v140, v141, v140
	v_add_f32_e32 v148, v148, v140
	ds_read_b128 v[140:143], v128 offset:25600
	s_waitcnt lgkmcnt(1)
	v_mul_f32_e32 v149, v95, v137
	v_mul_f32_e32 v137, v121, v137
	v_fmac_f32_e32 v149, v94, v136
	v_fmac_f32_e32 v137, v120, v136
	v_mul_f32_e32 v136, v79, v139
	v_mul_f32_e32 v150, v93, v139
	v_fmac_f32_e32 v136, v78, v138
	v_fmac_f32_e32 v150, v92, v138
	v_add_f32_e32 v136, v137, v136
	v_add_f32_e32 v149, v149, v150
	v_add_f32_e32 v150, 0, v136
	s_waitcnt lgkmcnt(0)
	v_mul_f32_e32 v136, v91, v141
	v_mul_f32_e32 v137, v89, v143
	v_fmac_f32_e32 v136, v90, v140
	v_fmac_f32_e32 v137, v88, v142
	v_add_f32_e32 v149, 0, v149
	v_add_f32_e32 v136, v136, v137
	v_add_f32_e32 v149, v149, v136
	v_mul_f32_e32 v141, v119, v141
	ds_read_b128 v[136:139], v128 offset:26624
	v_fmac_f32_e32 v141, v118, v140
	v_mul_f32_e32 v140, v75, v143
	v_fmac_f32_e32 v140, v74, v142
	v_add_f32_e32 v140, v141, v140
	v_add_f32_e32 v150, v150, v140
	ds_read_b128 v[140:143], v128 offset:27648
	s_waitcnt lgkmcnt(1)
	v_mul_f32_e32 v151, v87, v137
	v_mul_f32_e32 v137, v73, v137
	v_fmac_f32_e32 v151, v86, v136
	v_fmac_f32_e32 v137, v72, v136
	v_mul_f32_e32 v136, v69, v139
	v_fmac_f32_e32 v136, v68, v138
	v_mul_f32_e32 v152, v85, v139
	v_add_f32_e32 v136, v137, v136
	v_fmac_f32_e32 v152, v84, v138
	v_add_f32_e32 v150, v150, v136
	s_waitcnt lgkmcnt(0)
	v_mul_f32_e32 v136, v83, v141
	v_mul_f32_e32 v137, v81, v143
	v_add_f32_e32 v151, v151, v152
	v_fmac_f32_e32 v136, v82, v140
	v_fmac_f32_e32 v137, v80, v142
	v_add_f32_e32 v149, v149, v151
	v_add_f32_e32 v136, v136, v137
	v_add_f32_e32 v149, v149, v136
	v_mul_f32_e32 v141, v71, v141
	ds_read_b128 v[136:139], v128 offset:28672
	v_fmac_f32_e32 v141, v70, v140
	v_mul_f32_e32 v140, v67, v143
	v_fmac_f32_e32 v140, v66, v142
	v_add_f32_e32 v140, v141, v140
	v_add_f32_e32 v150, v150, v140
	ds_read_b128 v[140:143], v128 offset:29696
	s_waitcnt lgkmcnt(1)
; #define LAS __attribute__((address_space(3)))
; __device__ __forceinline__ void phase1(const Params& p, LAS unsigned char* lds, int tid, int lane, int wave) {
;     ...
;         for (int h = 0; h < 8; ++h) { float s0 = 0.f, s1 = 0.f;
; #pragma unroll
;             for (int j = 0; j < 4; ++j) { const f32x4 w = *(const LAS f32x4*)(wf + h * 1024 + 4 * lane + 256 * j);
;                 s0 += (v[0][j].x * w.x + v[0][j].y * w.y) + (v[0][j].z * w.z + v[0][j].w * w.w); s1 += (v[1][j].x * w.x + v[1][j].y * w.y) + (v[1][j].z * w.z + v[1][j].w * w.w); }
;             f[0][h] = s0; f[1][h] = s1; }
;         float g4[2][4], g2[2][2], z[2];
; #pragma unroll
;         for (int i = 0; i < 4; ++i)
; #pragma unroll
;             for (int q = 0; q < 2; ++q) { const float send = b5 ? f[q][i] : f[q][4 + i], keep = b5 ? f[q][4 + i] : f[q][i]; g4[q][i] = keep + __shfl_xor(send, 32); }
; #pragma unroll
;         for (int i = 0; i < 2; ++i)
; #pragma unroll
;             for (int q = 0; q < 2; ++q) { const float send = b4 ? g4[q][i] : g4[q][2 + i], keep = b4 ? g4[q][2 + i] : g4[q][i]; g2[q][i] = keep + __shfl_xor(send, 16); }
; #pragma unroll
;         for (int q = 0; q < 2; ++q) { const float send = b3 ? g2[q][0] : g2[q][1], keep = b3 ? g2[q][1] : g2[q][0]; z[q] = keep + __shfl_xor(send, 8); }
; #pragma unroll
;         for (int q = 0; q < 2; ++q) z[q] = xsum12(z[q]);
;         z[0] += __shfl_xor(z[0], 4); z[1] += __shfl_xor(z[1], 4);
;         if ((lane & 7) == 0) { const int h = lane >> 3; const float bf_ = p.b_f[h];
; #pragma unroll
;             for (int q = 0; q < 2; ++q) { const float zz = z[q] + bf_; logf[(size_t)ROW2(row, q) * 8 + h] = fminf(zz, 0.f) - __logf(1.f + __expf(-fabsf(zz))); } }
	v_mul_f32_e32 v95, v95, v137
	v_mul_f32_e32 v93, v93, v139
	v_fmac_f32_e32 v95, v94, v136
	v_fmac_f32_e32 v93, v92, v138
	v_add_f32_e32 v92, v95, v93
	v_mul_f32_e32 v93, v121, v137
	v_mul_f32_e32 v79, v79, v139
	v_fmac_f32_e32 v93, v120, v136
	v_fmac_f32_e32 v79, v78, v138
	v_add_f32_e32 v78, v93, v79
	s_waitcnt lgkmcnt(0)
	v_mul_f32_e32 v79, v91, v141
	v_mul_f32_e32 v89, v89, v143
	v_fmac_f32_e32 v79, v90, v140
	v_fmac_f32_e32 v89, v88, v142
	v_add_f32_e32 v92, 0, v92
	v_add_f32_e32 v79, v79, v89
	v_add_f32_e32 v79, v92, v79
	v_mul_f32_e32 v92, v119, v141
	v_mul_f32_e32 v75, v75, v143
	v_fmac_f32_e32 v92, v118, v140
	v_fmac_f32_e32 v75, v74, v142
	ds_read_b128 v[88:91], v128 offset:30720
	v_add_f32_e32 v74, v92, v75
	ds_read_b128 v[92:95], v128 offset:31744
	v_add_f32_e32 v78, 0, v78
	v_add_f32_e32 v74, v78, v74
	s_waitcnt lgkmcnt(1)
	v_mul_f32_e32 v73, v73, v89
	v_mul_f32_e32 v69, v69, v91
	s_waitcnt lgkmcnt(0)
	v_mul_f32_e32 v71, v71, v93
	v_mul_f32_e32 v67, v67, v95
	v_fmac_f32_e32 v71, v70, v92
	v_fmac_f32_e32 v67, v66, v94
	v_add_f32_e32 v66, v71, v67
	v_cndmask_b32_e64 v67, v129, v145, s[6:7]
	ds_bpermute_b32 v67, v123, v67
	v_cndmask_b32_e64 v70, v130, v146, s[6:7]
	v_fmac_f32_e32 v73, v72, v88
	v_fmac_f32_e32 v69, v68, v90
	ds_bpermute_b32 v70, v123, v70
	v_cndmask_b32_e64 v71, v131, v147, s[6:7]
	v_add_f32_e32 v68, v73, v69
	ds_bpermute_b32 v71, v123, v71
	v_add_f32_e32 v68, v74, v68
	v_add_f32_e32 v66, v68, v66
	v_cndmask_b32_e64 v68, v145, v129, s[6:7]
	s_waitcnt lgkmcnt(2)
	v_add_f32_e32 v67, v68, v67
	v_cndmask_b32_e64 v68, v146, v130, s[6:7]
	s_waitcnt lgkmcnt(1)
	v_add_f32_e32 v68, v68, v70
	v_cndmask_b32_e64 v70, v147, v131, s[6:7]
	s_waitcnt lgkmcnt(0)
	v_add_f32_e32 v70, v70, v71
	v_cndmask_b32_e64 v71, v132, v148, s[6:7]
	ds_bpermute_b32 v71, v123, v71
	v_cndmask_b32_e64 v73, v133, v149, s[6:7]
	ds_bpermute_b32 v73, v123, v73
	v_cndmask_b32_e64 v74, v134, v150, s[6:7]
	v_mul_f32_e32 v75, v87, v89
	v_mul_f32_e32 v78, v85, v91
	v_mul_f32_e32 v69, v83, v93
	v_mul_f32_e32 v72, v81, v95
	ds_bpermute_b32 v74, v123, v74
	v_fmac_f32_e32 v75, v86, v88
	v_fmac_f32_e32 v78, v84, v90
	v_fmac_f32_e32 v69, v82, v92
	v_fmac_f32_e32 v72, v80, v94
	v_add_f32_e32 v75, v75, v78
	v_add_f32_e32 v69, v69, v72
	v_cndmask_b32_e64 v72, v148, v132, s[6:7]
	v_add_f32_e32 v75, v79, v75
	s_waitcnt lgkmcnt(2)
	v_add_f32_e32 v71, v72, v71
	v_cndmask_b32_e64 v72, v149, v133, s[6:7]
	v_add_f32_e32 v69, v75, v69
	s_waitcnt lgkmcnt(1)
	v_add_f32_e32 v72, v72, v73
	v_cndmask_b32_e64 v73, v150, v134, s[6:7]
	s_waitcnt lgkmcnt(0)
	v_add_f32_e32 v73, v73, v74
	v_cndmask_b32_e64 v74, v135, v69, s[6:7]
	v_cndmask_b32_e64 v75, v144, v66, s[6:7]
	ds_bpermute_b32 v74, v123, v74
	ds_bpermute_b32 v75, v123, v75
	v_cndmask_b32_e64 v69, v69, v135, s[6:7]
	v_cndmask_b32_e64 v66, v66, v144, s[6:7]
	v_cndmask_b32_e64 v78, v67, v72, s[8:9]
	s_waitcnt lgkmcnt(1)
	v_add_f32_e32 v69, v69, v74
	s_waitcnt lgkmcnt(0)
	v_add_f32_e32 v66, v66, v75
	v_cndmask_b32_e64 v67, v72, v67, s[8:9]
	v_cndmask_b32_e64 v72, v68, v73, s[8:9]
	v_cndmask_b32_e64 v68, v73, v68, s[8:9]
	v_cndmask_b32_e64 v73, v70, v69, s[8:9]
	v_cndmask_b32_e64 v74, v71, v66, s[8:9]
	ds_bpermute_b32 v78, v122, v78
	ds_bpermute_b32 v72, v122, v72
	ds_bpermute_b32 v73, v122, v73
	ds_bpermute_b32 v74, v122, v74
	v_cndmask_b32_e64 v69, v69, v70, s[8:9]
	v_cndmask_b32_e64 v66, v66, v71, s[8:9]
	s_waitcnt lgkmcnt(3)
	v_add_f32_e32 v67, v67, v78
	s_waitcnt lgkmcnt(2)
	v_add_f32_e32 v68, v68, v72
	s_waitcnt lgkmcnt(1)
	v_add_f32_e32 v69, v69, v73
	s_waitcnt lgkmcnt(0)
	v_add_f32_e32 v66, v66, v74
	v_cndmask_b32_e64 v70, v67, v69, s[10:11]
	v_cndmask_b32_e64 v71, v68, v66, s[10:11]
	ds_bpermute_b32 v70, v117, v70
	ds_bpermute_b32 v71, v117, v71
	v_cndmask_b32_e64 v67, v69, v67, s[10:11]
	v_cndmask_b32_e64 v66, v66, v68, s[10:11]
	s_waitcnt lgkmcnt(1)
	v_add_f32_e32 v67, v67, v70
	s_waitcnt lgkmcnt(0)
	v_add_f32_e32 v68, v66, v71
	v_add_f32_dpp v66, v67, v67 quad_perm:[1,0,3,2] row_mask:0xf bank_mask:0xf bound_ctrl:1
	s_nop 0
	v_add_f32_dpp v67, v68, v68 quad_perm:[1,0,3,2] row_mask:0xf bank_mask:0xf bound_ctrl:1
	v_add_f32_dpp v66, v66, v66 quad_perm:[2,3,0,1] row_mask:0xf bank_mask:0xf bound_ctrl:1
	ds_bpermute_b32 v68, v97, v66
	v_add_f32_dpp v67, v67, v67 quad_perm:[2,3,0,1] row_mask:0xf bank_mask:0xf bound_ctrl:1
	ds_bpermute_b32 v69, v97, v67
	s_and_saveexec_b64 s[34:35], s[12:13]
	s_cbranch_execz .LBB0_194
	s_waitcnt lgkmcnt(1)
	v_add_f32_e32 v68, v66, v68
	s_waitcnt lgkmcnt(0)
	v_add_f32_e32 v69, v67, v69
	s_lshl_b64 s[14:15], s[14:15], 5
	v_lshl_add_u64 v[66:67], v[102:103], 0, s[14:15]
	v_lshl_add_u64 v[64:65], s[30:31], 0, v[110:111]
	v_add_f32_e32 v68, v68, v153
	v_add_f32_e32 v69, v69, v153
	v_mul_f32_e64 v70, |v68|, s28
	v_mul_f32_e64 v71, |v69|, s28
	v_exp_f32_e32 v70, v70
	v_exp_f32_e32 v71, v71
	v_min_f32_e32 v68, 0, v68
	v_min_f32_e32 v69, 0, v69
	v_add_f32_e32 v70, 1.0, v70
	v_add_f32_e32 v71, 1.0, v71
	v_cmp_gt_f32_e32 vcc, s5, v70
	v_cmp_gt_f32_e64 s[14:15], s5, v71
	s_nop 0
	v_cndmask_b32_e64 v72, 0, 32, vcc
	v_cndmask_b32_e64 v73, 0, 32, s[14:15]
	v_ldexp_f32 v70, v70, v72
	v_ldexp_f32 v71, v71, v73
	v_log_f32_e32 v70, v70
	v_log_f32_e32 v71, v71
	v_cndmask_b32_e32 v72, 0, v127, vcc
	v_cndmask_b32_e64 v73, 0, v127, s[14:15]
	v_mul_f32_e32 v74, 0x3f317217, v70
	v_mul_f32_e32 v75, 0x3f317217, v71
	v_fma_f32 v74, v70, s29, -v74
	v_fma_f32 v75, v71, s29, -v75
	v_fmac_f32_e32 v74, 0x3377d1cf, v70
	v_fmac_f32_e32 v75, 0x3377d1cf, v71
	v_fmac_f32_e32 v74, 0x3f317217, v70
	v_cmp_lt_f32_e64 vcc, |v70|, s36
	v_fmac_f32_e32 v75, 0x3f317217, v71
	s_nop 0
	v_cndmask_b32_e32 v70, v70, v74, vcc
	v_cmp_lt_f32_e64 vcc, |v71|, s36
	v_sub_f32_e32 v70, v70, v72
	v_sub_f32_e32 v68, v68, v70
	v_cndmask_b32_e32 v71, v71, v75, vcc
	v_sub_f32_e32 v71, v71, v73
	v_sub_f32_e32 v69, v69, v71
	global_store_dword v[64:65], v68, off sc1
	global_store_dword v[66:67], v69, off sc1
	s_branch .LBB0_194
